# comb12 + conv LayerNorm tail: each lane owns 8 contiguous channels so the bf16 rows are stored with 16-byte stores (8 instead of 16 per wave)
# baseline (speedup 1.0000x reference)
; #define LAS __attribute__((address_space(3)))
; __global__ void __launch_bounds__(NTHR, 2) fwd_megakernel(Args args) {
;     ...
;             __syncthreads();
; #pragma unroll
;             for (int rr = 0; rr < 4; ++rr) { const int r = wave * 4 + rr; f32x4 x[4]; float s = 0.f;
; #pragma unroll
;                 for (int j = 0; j < 4; ++j) { x[j] = *(const LAS f32x4*)(Os + r * CCH + j * 256 + 4 * lane); s += (x[j][0] + x[j][1]) + (x[j][2] + x[j][3]); }
;                 const float mean = wave_sum(s) * (1.0f / CCH); float q = 0.f;
.LBB0_562:
	v_lshlrev_b32_e32 v140, 4, v221
	v_add_u32_e32 v140, 0x20000, v140
	v_and_b32_e32 v141, 0xff, v221
	v_lshlrev_b32_e32 v141, 4, v141
	v_add_u32_e32 v141, 0x22000, v141
	ds_write_b128 v140, v[246:249]
	ds_write_b128 v141, v[250:253]
	s_waitcnt lgkmcnt(0)
	s_barrier
	v_lshlrev_b32_e32 v94, 1, v219
	v_add_u32_e32 v94, 0x20000, v94
	ds_read_b128 v[204:207], v94
	ds_read_b128 v[232:235], v94 offset:4096
	ds_read_b128 v[208:211], v94 offset:16
	ds_read_b128 v[236:239], v94 offset:4112
	ds_read_b128 v[212:215], v94 offset:2048
	ds_read_b128 v[240:243], v94 offset:6144
	ds_read_b128 v[228:231], v94 offset:2064
	ds_read_b128 v[0:3], v94 offset:6160
	ds_read_b128 v[4:7], v94 offset:8192
	ds_read_b128 v[8:11], v94 offset:8208
	ds_read_b128 v[12:15], v94 offset:10240
	ds_read_b128 v[16:19], v94 offset:10256
	v_lshl_add_u32 v98, v219, 1, s24
	v_lshl_add_u32 v99, v219, 1, s26
	v_lshl_add_u32 v100, v219, 1, s57
	v_lshl_add_u32 v101, v219, 1, s59
	ds_read_b128 v[140:143], v98
	ds_read_b128 v[144:147], v98 offset:16
	ds_read_b128 v[148:151], v98 offset:2048
	ds_read_b128 v[152:155], v98 offset:2064
	ds_read_b128 v[156:159], v99
	ds_read_b128 v[160:163], v99 offset:16
	ds_read_b128 v[164:167], v99 offset:2048
	ds_read_b128 v[168:171], v99 offset:2064
	ds_read_b128 v[172:175], v100
	ds_read_b128 v[176:179], v100 offset:16
	ds_read_b128 v[180:183], v100 offset:2048
	ds_read_b128 v[184:187], v100 offset:2064
	ds_read_b128 v[188:191], v101
	ds_read_b128 v[192:195], v101 offset:16
	ds_read_b128 v[196:199], v101 offset:2048
	ds_read_b128 v[200:203], v101 offset:2064
	v_lshrrev_b32_e32 v138, 1, v219
	v_mov_b32_e32 v139, 0
	s_add_i32 s2, s56, s62
	s_ashr_i32 s3, s2, 31
	s_lshl_b64 s[2:3], s[2:3], 12
	v_lshl_add_u64 v[126:127], v[32:33], 0, s[2:3]
	v_lshl_add_u64 v[126:127], v[126:127], 0, v[138:139]
	s_add_i32 s2, s25, s62
	s_ashr_i32 s3, s2, 31
	s_lshl_b64 s[2:3], s[2:3], 12
	v_lshl_add_u64 v[128:129], v[32:33], 0, s[2:3]
	v_lshl_add_u64 v[128:129], v[128:129], 0, v[138:139]
	s_add_i32 s2, s27, s62
	s_ashr_i32 s3, s2, 31
	s_lshl_b64 s[2:3], s[2:3], 12
	v_lshl_add_u64 v[130:131], v[32:33], 0, s[2:3]
	v_lshl_add_u64 v[130:131], v[130:131], 0, v[138:139]
	s_add_i32 s2, s58, s62
	s_ashr_i32 s3, s2, 31
	s_lshl_b64 s[2:3], s[2:3], 12
	v_lshl_add_u64 v[132:133], v[32:33], 0, s[2:3]
	v_lshl_add_u64 v[132:133], v[132:133], 0, v[138:139]
	s_waitcnt lgkmcnt(0)
	v_add_f32_e32 v110, v140, v141
	v_add_f32_e32 v111, v142, v143
	v_add_f32_e32 v114, v156, v157
	v_add_f32_e32 v115, v158, v159
	v_add_f32_e32 v118, v172, v173
	v_add_f32_e32 v119, v174, v175
	v_add_f32_e32 v122, v188, v189
	v_add_f32_e32 v123, v190, v191
	v_add_f32_e32 v110, v110, v111
	v_add_f32_e32 v114, v114, v115
	v_add_f32_e32 v118, v118, v119
	v_add_f32_e32 v122, v122, v123
	v_mov_b32_e32 v94, v110
	v_mov_b32_e32 v95, v114
	v_mov_b32_e32 v96, v118
	v_mov_b32_e32 v97, v122
	v_add_f32_e32 v110, v144, v145
	v_add_f32_e32 v111, v146, v147
	v_add_f32_e32 v114, v160, v161
	v_add_f32_e32 v115, v162, v163
	v_add_f32_e32 v118, v176, v177
	v_add_f32_e32 v119, v178, v179
	v_add_f32_e32 v122, v192, v193
	v_add_f32_e32 v123, v194, v195
	v_add_f32_e32 v110, v110, v111
	v_add_f32_e32 v114, v114, v115
	v_add_f32_e32 v118, v118, v119
	v_add_f32_e32 v122, v122, v123
	v_add_f32_e32 v94, v94, v110
	v_add_f32_e32 v95, v95, v114
	v_add_f32_e32 v96, v96, v118
	v_add_f32_e32 v97, v97, v122
	v_add_f32_e32 v110, v148, v149
	v_add_f32_e32 v111, v150, v151
	v_add_f32_e32 v114, v164, v165
	v_add_f32_e32 v115, v166, v167
	v_add_f32_e32 v118, v180, v181
	v_add_f32_e32 v119, v182, v183
	v_add_f32_e32 v122, v196, v197
	v_add_f32_e32 v123, v198, v199
	v_add_f32_e32 v110, v110, v111
	v_add_f32_e32 v114, v114, v115
	v_add_f32_e32 v118, v118, v119
	v_add_f32_e32 v122, v122, v123
	v_add_f32_e32 v94, v94, v110
	v_add_f32_e32 v95, v95, v114
	v_add_f32_e32 v96, v96, v118
	v_add_f32_e32 v97, v97, v122
	v_add_f32_e32 v110, v152, v153
	v_add_f32_e32 v111, v154, v155
	v_add_f32_e32 v114, v168, v169
	v_add_f32_e32 v115, v170, v171
	v_add_f32_e32 v118, v184, v185
	v_add_f32_e32 v119, v186, v187
	v_add_f32_e32 v122, v200, v201
	v_add_f32_e32 v123, v202, v203
	v_add_f32_e32 v110, v110, v111
	v_add_f32_e32 v114, v114, v115
	v_add_f32_e32 v118, v118, v119
	v_add_f32_e32 v122, v122, v123
	v_add_f32_e32 v94, v94, v110
	v_add_f32_e32 v95, v95, v114
	v_add_f32_e32 v96, v96, v118
	v_add_f32_e32 v97, v97, v122
	s_nop 1
	v_add_f32_dpp v98, v94, v94 quad_perm:[1,0,3,2] row_mask:0xf bank_mask:0xf
	v_add_f32_dpp v99, v95, v95 quad_perm:[1,0,3,2] row_mask:0xf bank_mask:0xf
	v_add_f32_dpp v100, v96, v96 quad_perm:[1,0,3,2] row_mask:0xf bank_mask:0xf
	v_add_f32_dpp v101, v97, v97 quad_perm:[1,0,3,2] row_mask:0xf bank_mask:0xf
	v_mov_b32_e32 v94, v98
	v_mov_b32_e32 v95, v99
	v_mov_b32_e32 v96, v100
	v_mov_b32_e32 v97, v101
	s_nop 1
	v_add_f32_dpp v98, v94, v94 quad_perm:[2,3,0,1] row_mask:0xf bank_mask:0xf
	v_add_f32_dpp v99, v95, v95 quad_perm:[2,3,0,1] row_mask:0xf bank_mask:0xf
	v_add_f32_dpp v100, v96, v96 quad_perm:[2,3,0,1] row_mask:0xf bank_mask:0xf
	v_add_f32_dpp v101, v97, v97 quad_perm:[2,3,0,1] row_mask:0xf bank_mask:0xf
	v_mov_b32_e32 v94, v98
	v_mov_b32_e32 v95, v99
	v_mov_b32_e32 v96, v100
	v_mov_b32_e32 v97, v101
	s_nop 1
	v_add_f32_dpp v98, v94, v94 row_half_mirror row_mask:0xf bank_mask:0xf
	v_add_f32_dpp v99, v95, v95 row_half_mirror row_mask:0xf bank_mask:0xf
	v_add_f32_dpp v100, v96, v96 row_half_mirror row_mask:0xf bank_mask:0xf
	v_add_f32_dpp v101, v97, v97 row_half_mirror row_mask:0xf bank_mask:0xf
	v_mov_b32_e32 v94, v98
	v_mov_b32_e32 v95, v99
	v_mov_b32_e32 v96, v100
	v_mov_b32_e32 v97, v101
	s_nop 1
	v_add_f32_dpp v98, v94, v94 row_mirror row_mask:0xf bank_mask:0xf
; __device__ __forceinline__ float wave_sum(float v) {
; #pragma unroll
;     for (int o = 1; o < 64; o <<= 1) v += __shfl_xor(v, o);
;     return v;
; __global__ void __launch_bounds__(NTHR, 2) fwd_megakernel(Args args) {
;     ...
;                 const float mean = wave_sum(s) * (1.0f / CCH); float q = 0.f;
; #pragma unroll
;                 for (int j = 0; j < 4; ++j) { x[j] = x[j] - mean; q += (x[j][0] * x[j][0] + x[j][1] * x[j][1]) + (x[j][2] * x[j][2] + x[j][3] * x[j][3]); }
	v_add_f32_dpp v99, v95, v95 row_mirror row_mask:0xf bank_mask:0xf
	v_add_f32_dpp v100, v96, v96 row_mirror row_mask:0xf bank_mask:0xf
	v_add_f32_dpp v101, v97, v97 row_mirror row_mask:0xf bank_mask:0xf
	v_mov_b32_e32 v94, v98
	v_mov_b32_e32 v95, v99
	v_mov_b32_e32 v96, v100
	v_mov_b32_e32 v97, v101
	v_mov_b32_e32 v98, v94
	v_mov_b32_e32 v99, v95
	v_mov_b32_e32 v100, v96
	v_mov_b32_e32 v101, v97
	s_nop 1
	v_permlane16_swap_b32_e32 v94, v98
	v_permlane16_swap_b32_e32 v95, v99
	v_permlane16_swap_b32_e32 v96, v100
	v_permlane16_swap_b32_e32 v97, v101
	s_nop 1
	v_add_f32_e32 v94, v94, v98
	v_add_f32_e32 v95, v95, v99
	v_add_f32_e32 v96, v96, v100
	v_add_f32_e32 v97, v97, v101
	v_mov_b32_e32 v98, v94
	v_mov_b32_e32 v99, v95
	v_mov_b32_e32 v100, v96
	v_mov_b32_e32 v101, v97
	s_nop 1
	v_permlane32_swap_b32_e32 v94, v98
	v_permlane32_swap_b32_e32 v95, v99
	v_permlane32_swap_b32_e32 v96, v100
	v_permlane32_swap_b32_e32 v97, v101
	s_nop 1
	v_add_f32_e32 v94, v94, v98
	v_add_f32_e32 v95, v95, v99
	v_add_f32_e32 v96, v96, v100
	v_add_f32_e32 v97, v97, v101
	v_fmamk_f32 v140, v94, 0xba800000, v140
	v_fmamk_f32 v141, v94, 0xba800000, v141
	v_fmamk_f32 v142, v94, 0xba800000, v142
	v_fmamk_f32 v143, v94, 0xba800000, v143
	v_fmamk_f32 v144, v94, 0xba800000, v144
	v_fmamk_f32 v145, v94, 0xba800000, v145
	v_fmamk_f32 v146, v94, 0xba800000, v146
	v_fmamk_f32 v147, v94, 0xba800000, v147
	v_fmamk_f32 v148, v94, 0xba800000, v148
	v_fmamk_f32 v149, v94, 0xba800000, v149
	v_fmamk_f32 v150, v94, 0xba800000, v150
	v_fmamk_f32 v151, v94, 0xba800000, v151
	v_fmamk_f32 v152, v94, 0xba800000, v152
	v_fmamk_f32 v153, v94, 0xba800000, v153
	v_fmamk_f32 v154, v94, 0xba800000, v154
	v_fmamk_f32 v155, v94, 0xba800000, v155
	v_fmamk_f32 v156, v95, 0xba800000, v156
	v_fmamk_f32 v157, v95, 0xba800000, v157
	v_fmamk_f32 v158, v95, 0xba800000, v158
	v_fmamk_f32 v159, v95, 0xba800000, v159
	v_fmamk_f32 v160, v95, 0xba800000, v160
	v_fmamk_f32 v161, v95, 0xba800000, v161
	v_fmamk_f32 v162, v95, 0xba800000, v162
	v_fmamk_f32 v163, v95, 0xba800000, v163
	v_fmamk_f32 v164, v95, 0xba800000, v164
	v_fmamk_f32 v165, v95, 0xba800000, v165
	v_fmamk_f32 v166, v95, 0xba800000, v166
	v_fmamk_f32 v167, v95, 0xba800000, v167
	v_fmamk_f32 v168, v95, 0xba800000, v168
	v_fmamk_f32 v169, v95, 0xba800000, v169
	v_fmamk_f32 v170, v95, 0xba800000, v170
	v_fmamk_f32 v171, v95, 0xba800000, v171
	v_fmamk_f32 v172, v96, 0xba800000, v172
	v_fmamk_f32 v173, v96, 0xba800000, v173
	v_fmamk_f32 v174, v96, 0xba800000, v174
	v_fmamk_f32 v175, v96, 0xba800000, v175
	v_fmamk_f32 v176, v96, 0xba800000, v176
	v_fmamk_f32 v177, v96, 0xba800000, v177
	v_fmamk_f32 v178, v96, 0xba800000, v178
	v_fmamk_f32 v179, v96, 0xba800000, v179
	v_fmamk_f32 v180, v96, 0xba800000, v180
	v_fmamk_f32 v181, v96, 0xba800000, v181
	v_fmamk_f32 v182, v96, 0xba800000, v182
	v_fmamk_f32 v183, v96, 0xba800000, v183
	v_fmamk_f32 v184, v96, 0xba800000, v184
	v_fmamk_f32 v185, v96, 0xba800000, v185
	v_fmamk_f32 v186, v96, 0xba800000, v186
	v_fmamk_f32 v187, v96, 0xba800000, v187
	v_fmamk_f32 v188, v97, 0xba800000, v188
	v_fmamk_f32 v189, v97, 0xba800000, v189
	v_fmamk_f32 v190, v97, 0xba800000, v190
	v_fmamk_f32 v191, v97, 0xba800000, v191
	v_fmamk_f32 v192, v97, 0xba800000, v192
	v_fmamk_f32 v193, v97, 0xba800000, v193
	v_fmamk_f32 v194, v97, 0xba800000, v194
	v_fmamk_f32 v195, v97, 0xba800000, v195
	v_fmamk_f32 v196, v97, 0xba800000, v196
	v_fmamk_f32 v197, v97, 0xba800000, v197
	v_fmamk_f32 v198, v97, 0xba800000, v198
	v_fmamk_f32 v199, v97, 0xba800000, v199
	v_fmamk_f32 v200, v97, 0xba800000, v200
	v_fmamk_f32 v201, v97, 0xba800000, v201
	v_fmamk_f32 v202, v97, 0xba800000, v202
	v_fmamk_f32 v203, v97, 0xba800000, v203
	v_mul_f32_e32 v110, v140, v140
	v_mul_f32_e32 v111, v142, v142
	v_mul_f32_e32 v114, v156, v156
	v_mul_f32_e32 v115, v158, v158
	v_mul_f32_e32 v118, v172, v172
	v_mul_f32_e32 v119, v174, v174
	v_mul_f32_e32 v122, v188, v188
	v_mul_f32_e32 v123, v190, v190
	v_fmac_f32_e32 v110, v141, v141
	v_fmac_f32_e32 v111, v143, v143
	v_fmac_f32_e32 v114, v157, v157
	v_fmac_f32_e32 v115, v159, v159
	v_fmac_f32_e32 v118, v173, v173
	v_fmac_f32_e32 v119, v175, v175
	v_fmac_f32_e32 v122, v189, v189
	v_fmac_f32_e32 v123, v191, v191
	v_add_f32_e32 v110, v110, v111
	v_add_f32_e32 v114, v114, v115
	v_add_f32_e32 v118, v118, v119
	v_add_f32_e32 v122, v122, v123
	v_mov_b32_e32 v102, v110
	v_mov_b32_e32 v103, v114
	v_mov_b32_e32 v104, v118
	v_mov_b32_e32 v105, v122
	v_mul_f32_e32 v110, v144, v144
	v_mul_f32_e32 v111, v146, v146
	v_mul_f32_e32 v114, v160, v160
	v_mul_f32_e32 v115, v162, v162
	v_mul_f32_e32 v118, v176, v176
	v_mul_f32_e32 v119, v178, v178
	v_mul_f32_e32 v122, v192, v192
	v_mul_f32_e32 v123, v194, v194
	v_fmac_f32_e32 v110, v145, v145
	v_fmac_f32_e32 v111, v147, v147
	v_fmac_f32_e32 v114, v161, v161
	v_fmac_f32_e32 v115, v163, v163
	v_fmac_f32_e32 v118, v177, v177
	v_fmac_f32_e32 v119, v179, v179
	v_fmac_f32_e32 v122, v193, v193
	v_fmac_f32_e32 v123, v195, v195
	v_add_f32_e32 v110, v110, v111
	v_add_f32_e32 v114, v114, v115
	v_add_f32_e32 v118, v118, v119
	v_add_f32_e32 v122, v122, v123
	v_add_f32_e32 v102, v102, v110
	v_add_f32_e32 v103, v103, v114
	v_add_f32_e32 v104, v104, v118
	v_add_f32_e32 v105, v105, v122
	v_mul_f32_e32 v110, v148, v148
	v_mul_f32_e32 v111, v150, v150
	v_mul_f32_e32 v114, v164, v164
	v_mul_f32_e32 v115, v166, v166
	v_mul_f32_e32 v118, v180, v180
	v_mul_f32_e32 v119, v182, v182
	v_mul_f32_e32 v122, v196, v196
	v_mul_f32_e32 v123, v198, v198
	v_fmac_f32_e32 v110, v149, v149
	v_fmac_f32_e32 v111, v151, v151
	v_fmac_f32_e32 v114, v165, v165
	v_fmac_f32_e32 v115, v167, v167
	v_fmac_f32_e32 v118, v181, v181
; __device__ __forceinline__ float sigmoidf_(float x) { return fast_rcp(1.0f + fast_exp2(-1.4426950408889634f * x)); }
; #define KIN(i) (*(const float* const __attribute__((address_space(4)))*)(kp + kz + 8 * (i)))
; __global__ void __launch_bounds__(NTHR, 2) fwd_megakernel(Args args) {
;     ...
;                 for (int j = 0; j < 4; ++j) { x[j] = x[j] - mean; q += (x[j][0] * x[j][0] + x[j][1] * x[j][1]) + (x[j][2] * x[j][2] + x[j][3] * x[j][3]); }
;                 const float rstd = rsqrtf(wave_sum(q) * (1.0f / CCH) + LN_EPS); float z2 = 0.f;
; #pragma unroll
;                 for (int j = 0; j < 4; ++j) { const f32x4 gg = *(const f32x4*)(KIN(I_CONV_LN_G) + j * 256 + 4 * lane), bb = *(const f32x4*)(KIN(I_CONV_LN_B) + j * 256 + 4 * lane);
;                     f32x4 y = x[j] * rstd * gg + bb;
; #pragma unroll
;                     for (int e = 0; e < 4; ++e) { y[e] = y[e] * sigmoidf_(y[e]); z2 += y[e] * y[e]; }
	v_fmac_f32_e32 v119, v183, v183
	v_fmac_f32_e32 v122, v197, v197
	v_fmac_f32_e32 v123, v199, v199
	v_add_f32_e32 v110, v110, v111
	v_add_f32_e32 v114, v114, v115
	v_add_f32_e32 v118, v118, v119
	v_add_f32_e32 v122, v122, v123
	v_add_f32_e32 v102, v102, v110
	v_add_f32_e32 v103, v103, v114
	v_add_f32_e32 v104, v104, v118
	v_add_f32_e32 v105, v105, v122
	v_mul_f32_e32 v110, v152, v152
	v_mul_f32_e32 v111, v154, v154
	v_mul_f32_e32 v114, v168, v168
	v_mul_f32_e32 v115, v170, v170
	v_mul_f32_e32 v118, v184, v184
	v_mul_f32_e32 v119, v186, v186
	v_mul_f32_e32 v122, v200, v200
	v_mul_f32_e32 v123, v202, v202
	v_fmac_f32_e32 v110, v153, v153
	v_fmac_f32_e32 v111, v155, v155
	v_fmac_f32_e32 v114, v169, v169
	v_fmac_f32_e32 v115, v171, v171
	v_fmac_f32_e32 v118, v185, v185
	v_fmac_f32_e32 v119, v187, v187
	v_fmac_f32_e32 v122, v201, v201
	v_fmac_f32_e32 v123, v203, v203
	v_add_f32_e32 v110, v110, v111
	v_add_f32_e32 v114, v114, v115
	v_add_f32_e32 v118, v118, v119
	v_add_f32_e32 v122, v122, v123
	v_add_f32_e32 v102, v102, v110
	v_add_f32_e32 v103, v103, v114
	v_add_f32_e32 v104, v104, v118
	v_add_f32_e32 v105, v105, v122
	s_nop 1
	v_add_f32_dpp v98, v102, v102 quad_perm:[1,0,3,2] row_mask:0xf bank_mask:0xf
	v_add_f32_dpp v99, v103, v103 quad_perm:[1,0,3,2] row_mask:0xf bank_mask:0xf
	v_add_f32_dpp v100, v104, v104 quad_perm:[1,0,3,2] row_mask:0xf bank_mask:0xf
	v_add_f32_dpp v101, v105, v105 quad_perm:[1,0,3,2] row_mask:0xf bank_mask:0xf
	v_mov_b32_e32 v102, v98
	v_mov_b32_e32 v103, v99
	v_mov_b32_e32 v104, v100
	v_mov_b32_e32 v105, v101
	s_nop 1
	v_add_f32_dpp v98, v102, v102 quad_perm:[2,3,0,1] row_mask:0xf bank_mask:0xf
	v_add_f32_dpp v99, v103, v103 quad_perm:[2,3,0,1] row_mask:0xf bank_mask:0xf
	v_add_f32_dpp v100, v104, v104 quad_perm:[2,3,0,1] row_mask:0xf bank_mask:0xf
	v_add_f32_dpp v101, v105, v105 quad_perm:[2,3,0,1] row_mask:0xf bank_mask:0xf
	v_mov_b32_e32 v102, v98
	v_mov_b32_e32 v103, v99
	v_mov_b32_e32 v104, v100
	v_mov_b32_e32 v105, v101
	s_nop 1
	v_add_f32_dpp v98, v102, v102 row_half_mirror row_mask:0xf bank_mask:0xf
	v_add_f32_dpp v99, v103, v103 row_half_mirror row_mask:0xf bank_mask:0xf
	v_add_f32_dpp v100, v104, v104 row_half_mirror row_mask:0xf bank_mask:0xf
	v_add_f32_dpp v101, v105, v105 row_half_mirror row_mask:0xf bank_mask:0xf
	v_mov_b32_e32 v102, v98
	v_mov_b32_e32 v103, v99
	v_mov_b32_e32 v104, v100
	v_mov_b32_e32 v105, v101
	s_nop 1
	v_add_f32_dpp v98, v102, v102 row_mirror row_mask:0xf bank_mask:0xf
	v_add_f32_dpp v99, v103, v103 row_mirror row_mask:0xf bank_mask:0xf
	v_add_f32_dpp v100, v104, v104 row_mirror row_mask:0xf bank_mask:0xf
	v_add_f32_dpp v101, v105, v105 row_mirror row_mask:0xf bank_mask:0xf
	v_mov_b32_e32 v102, v98
	v_mov_b32_e32 v103, v99
	v_mov_b32_e32 v104, v100
	v_mov_b32_e32 v105, v101
	v_mov_b32_e32 v98, v102
	v_mov_b32_e32 v99, v103
	v_mov_b32_e32 v100, v104
	v_mov_b32_e32 v101, v105
	s_nop 1
	v_permlane16_swap_b32_e32 v102, v98
	v_permlane16_swap_b32_e32 v103, v99
	v_permlane16_swap_b32_e32 v104, v100
	v_permlane16_swap_b32_e32 v105, v101
	s_nop 1
	v_add_f32_e32 v102, v102, v98
	v_add_f32_e32 v103, v103, v99
	v_add_f32_e32 v104, v104, v100
	v_add_f32_e32 v105, v105, v101
	v_mov_b32_e32 v98, v102
	v_mov_b32_e32 v99, v103
	v_mov_b32_e32 v100, v104
	v_mov_b32_e32 v101, v105
	s_nop 1
	v_permlane32_swap_b32_e32 v102, v98
	v_permlane32_swap_b32_e32 v103, v99
	v_permlane32_swap_b32_e32 v104, v100
	v_permlane32_swap_b32_e32 v105, v101
	s_nop 1
	v_add_f32_e32 v102, v102, v98
	v_add_f32_e32 v103, v103, v99
	v_add_f32_e32 v104, v104, v100
	v_add_f32_e32 v105, v105, v101
	v_fmamk_f32 v106, v102, 0x3a800000, v226
	v_fmamk_f32 v107, v103, 0x3a800000, v226
	v_fmamk_f32 v108, v104, 0x3a800000, v226
	v_fmamk_f32 v109, v105, 0x3a800000, v226
	v_rsq_f32_e32 v106, v106
	v_rsq_f32_e32 v107, v107
	v_rsq_f32_e32 v108, v108
	v_rsq_f32_e32 v109, v109
	s_waitcnt vmcnt(0)
	v_mov_b32_e32 v102, 0
	v_mov_b32_e32 v103, 0
	v_mov_b32_e32 v104, 0
	v_mov_b32_e32 v105, 0
	v_mul_f32_e32 v140, v140, v106
	v_mul_f32_e32 v141, v141, v106
	v_mul_f32_e32 v142, v142, v106
	v_mul_f32_e32 v143, v143, v106
	v_mul_f32_e32 v156, v156, v107
	v_mul_f32_e32 v157, v157, v107
	v_mul_f32_e32 v158, v158, v107
	v_mul_f32_e32 v159, v159, v107
	v_mul_f32_e32 v172, v172, v108
	v_mul_f32_e32 v173, v173, v108
	v_mul_f32_e32 v174, v174, v108
	v_mul_f32_e32 v175, v175, v108
	v_mul_f32_e32 v188, v188, v109
	v_mul_f32_e32 v189, v189, v109
	v_mul_f32_e32 v190, v190, v109
	v_mul_f32_e32 v191, v191, v109
	v_fma_f32 v140, v140, v204, v232
	v_fma_f32 v141, v141, v205, v233
	v_fma_f32 v142, v142, v206, v234
	v_fma_f32 v143, v143, v207, v235
	v_fma_f32 v156, v156, v204, v232
	v_fma_f32 v157, v157, v205, v233
	v_fma_f32 v158, v158, v206, v234
	v_fma_f32 v159, v159, v207, v235
	v_fma_f32 v172, v172, v204, v232
	v_fma_f32 v173, v173, v205, v233
	v_fma_f32 v174, v174, v206, v234
	v_fma_f32 v175, v175, v207, v235
	v_fma_f32 v188, v188, v204, v232
	v_fma_f32 v189, v189, v205, v233
	v_fma_f32 v190, v190, v206, v234
	v_fma_f32 v191, v191, v207, v235
	v_mul_f32_e32 v110, 0xbfb8aa3b, v140
	v_mul_f32_e32 v111, 0xbfb8aa3b, v141
	v_mul_f32_e32 v112, 0xbfb8aa3b, v142
	v_mul_f32_e32 v113, 0xbfb8aa3b, v143
	v_mul_f32_e32 v114, 0xbfb8aa3b, v156
	v_mul_f32_e32 v115, 0xbfb8aa3b, v157
	v_mul_f32_e32 v116, 0xbfb8aa3b, v158
	v_mul_f32_e32 v117, 0xbfb8aa3b, v159
	v_mul_f32_e32 v118, 0xbfb8aa3b, v172
	v_mul_f32_e32 v119, 0xbfb8aa3b, v173
	v_mul_f32_e32 v120, 0xbfb8aa3b, v174
	v_mul_f32_e32 v121, 0xbfb8aa3b, v175
	v_mul_f32_e32 v122, 0xbfb8aa3b, v188
	v_mul_f32_e32 v123, 0xbfb8aa3b, v189
	v_mul_f32_e32 v124, 0xbfb8aa3b, v190
	v_mul_f32_e32 v125, 0xbfb8aa3b, v191
	v_exp_f32_e32 v110, v110
; __device__ __forceinline__ float sigmoidf_(float x) { return fast_rcp(1.0f + fast_exp2(-1.4426950408889634f * x)); }
; #define KIN(i) (*(const float* const __attribute__((address_space(4)))*)(kp + kz + 8 * (i)))
; __global__ void __launch_bounds__(NTHR, 2) fwd_megakernel(Args args) {
;     ...
;                 for (int j = 0; j < 4; ++j) { const f32x4 gg = *(const f32x4*)(KIN(I_CONV_LN_G) + j * 256 + 4 * lane), bb = *(const f32x4*)(KIN(I_CONV_LN_B) + j * 256 + 4 * lane);
;                     f32x4 y = x[j] * rstd * gg + bb;
; #pragma unroll
;                     for (int e = 0; e < 4; ++e) { y[e] = y[e] * sigmoidf_(y[e]); z2 += y[e] * y[e]; }
;                     x[j] = y; }
	v_exp_f32_e32 v111, v111
	v_exp_f32_e32 v112, v112
	v_exp_f32_e32 v113, v113
	v_exp_f32_e32 v114, v114
	v_exp_f32_e32 v115, v115
	v_exp_f32_e32 v116, v116
	v_exp_f32_e32 v117, v117
	v_exp_f32_e32 v118, v118
	v_exp_f32_e32 v119, v119
	v_exp_f32_e32 v120, v120
	v_exp_f32_e32 v121, v121
	v_exp_f32_e32 v122, v122
	v_exp_f32_e32 v123, v123
	v_exp_f32_e32 v124, v124
	v_exp_f32_e32 v125, v125
	v_add_f32_e32 v110, 1.0, v110
	v_add_f32_e32 v111, 1.0, v111
	v_add_f32_e32 v112, 1.0, v112
	v_add_f32_e32 v113, 1.0, v113
	v_add_f32_e32 v114, 1.0, v114
	v_add_f32_e32 v115, 1.0, v115
	v_add_f32_e32 v116, 1.0, v116
	v_add_f32_e32 v117, 1.0, v117
	v_add_f32_e32 v118, 1.0, v118
	v_add_f32_e32 v119, 1.0, v119
	v_add_f32_e32 v120, 1.0, v120
	v_add_f32_e32 v121, 1.0, v121
	v_add_f32_e32 v122, 1.0, v122
	v_add_f32_e32 v123, 1.0, v123
	v_add_f32_e32 v124, 1.0, v124
	v_add_f32_e32 v125, 1.0, v125
	v_rcp_f32_e32 v110, v110
	v_rcp_f32_e32 v111, v111
	v_rcp_f32_e32 v112, v112
	v_rcp_f32_e32 v113, v113
	v_rcp_f32_e32 v114, v114
	v_rcp_f32_e32 v115, v115
	v_rcp_f32_e32 v116, v116
	v_rcp_f32_e32 v117, v117
	v_rcp_f32_e32 v118, v118
	v_rcp_f32_e32 v119, v119
	v_rcp_f32_e32 v120, v120
	v_rcp_f32_e32 v121, v121
	v_rcp_f32_e32 v122, v122
	v_rcp_f32_e32 v123, v123
	v_rcp_f32_e32 v124, v124
	v_rcp_f32_e32 v125, v125
	v_mul_f32_e32 v140, v140, v110
	v_mul_f32_e32 v141, v141, v111
	v_mul_f32_e32 v142, v142, v112
	v_mul_f32_e32 v143, v143, v113
	v_mul_f32_e32 v156, v156, v114
	v_mul_f32_e32 v157, v157, v115
	v_mul_f32_e32 v158, v158, v116
	v_mul_f32_e32 v159, v159, v117
	v_mul_f32_e32 v172, v172, v118
	v_mul_f32_e32 v173, v173, v119
	v_mul_f32_e32 v174, v174, v120
	v_mul_f32_e32 v175, v175, v121
	v_mul_f32_e32 v188, v188, v122
	v_mul_f32_e32 v189, v189, v123
	v_mul_f32_e32 v190, v190, v124
	v_mul_f32_e32 v191, v191, v125
	v_fmac_f32_e32 v102, v140, v140
	v_fmac_f32_e32 v103, v156, v156
	v_fmac_f32_e32 v104, v172, v172
	v_fmac_f32_e32 v105, v188, v188
	v_fmac_f32_e32 v102, v141, v141
	v_fmac_f32_e32 v103, v157, v157
	v_fmac_f32_e32 v104, v173, v173
	v_fmac_f32_e32 v105, v189, v189
	v_fmac_f32_e32 v102, v142, v142
	v_fmac_f32_e32 v103, v158, v158
	v_fmac_f32_e32 v104, v174, v174
	v_fmac_f32_e32 v105, v190, v190
	v_fmac_f32_e32 v102, v143, v143
	v_fmac_f32_e32 v103, v159, v159
	v_fmac_f32_e32 v104, v175, v175
	v_fmac_f32_e32 v105, v191, v191
	v_mul_f32_e32 v144, v144, v106
	v_mul_f32_e32 v145, v145, v106
	v_mul_f32_e32 v146, v146, v106
	v_mul_f32_e32 v147, v147, v106
	v_mul_f32_e32 v160, v160, v107
	v_mul_f32_e32 v161, v161, v107
	v_mul_f32_e32 v162, v162, v107
	v_mul_f32_e32 v163, v163, v107
	v_mul_f32_e32 v176, v176, v108
	v_mul_f32_e32 v177, v177, v108
	v_mul_f32_e32 v178, v178, v108
	v_mul_f32_e32 v179, v179, v108
	v_mul_f32_e32 v192, v192, v109
	v_mul_f32_e32 v193, v193, v109
	v_mul_f32_e32 v194, v194, v109
	v_mul_f32_e32 v195, v195, v109
	v_fma_f32 v144, v144, v208, v236
	v_fma_f32 v145, v145, v209, v237
	v_fma_f32 v146, v146, v210, v238
	v_fma_f32 v147, v147, v211, v239
	v_fma_f32 v160, v160, v208, v236
	v_fma_f32 v161, v161, v209, v237
	v_fma_f32 v162, v162, v210, v238
	v_fma_f32 v163, v163, v211, v239
	v_fma_f32 v176, v176, v208, v236
	v_fma_f32 v177, v177, v209, v237
	v_fma_f32 v178, v178, v210, v238
	v_fma_f32 v179, v179, v211, v239
	v_fma_f32 v192, v192, v208, v236
	v_fma_f32 v193, v193, v209, v237
	v_fma_f32 v194, v194, v210, v238
	v_fma_f32 v195, v195, v211, v239
	v_mul_f32_e32 v110, 0xbfb8aa3b, v144
	v_mul_f32_e32 v111, 0xbfb8aa3b, v145
	v_mul_f32_e32 v112, 0xbfb8aa3b, v146
	v_mul_f32_e32 v113, 0xbfb8aa3b, v147
	v_mul_f32_e32 v114, 0xbfb8aa3b, v160
	v_mul_f32_e32 v115, 0xbfb8aa3b, v161
	v_mul_f32_e32 v116, 0xbfb8aa3b, v162
	v_mul_f32_e32 v117, 0xbfb8aa3b, v163
	v_mul_f32_e32 v118, 0xbfb8aa3b, v176
	v_mul_f32_e32 v119, 0xbfb8aa3b, v177
	v_mul_f32_e32 v120, 0xbfb8aa3b, v178
	v_mul_f32_e32 v121, 0xbfb8aa3b, v179
	v_mul_f32_e32 v122, 0xbfb8aa3b, v192
	v_mul_f32_e32 v123, 0xbfb8aa3b, v193
	v_mul_f32_e32 v124, 0xbfb8aa3b, v194
	v_mul_f32_e32 v125, 0xbfb8aa3b, v195
	v_exp_f32_e32 v110, v110
	v_exp_f32_e32 v111, v111
	v_exp_f32_e32 v112, v112
	v_exp_f32_e32 v113, v113
	v_exp_f32_e32 v114, v114
	v_exp_f32_e32 v115, v115
	v_exp_f32_e32 v116, v116
	v_exp_f32_e32 v117, v117
	v_exp_f32_e32 v118, v118
	v_exp_f32_e32 v119, v119
	v_exp_f32_e32 v120, v120
	v_exp_f32_e32 v121, v121
	v_exp_f32_e32 v122, v122
	v_exp_f32_e32 v123, v123
	v_exp_f32_e32 v124, v124
	v_exp_f32_e32 v125, v125
	v_add_f32_e32 v110, 1.0, v110
	v_add_f32_e32 v111, 1.0, v111
	v_add_f32_e32 v112, 1.0, v112
	v_add_f32_e32 v113, 1.0, v113
	v_add_f32_e32 v114, 1.0, v114
	v_add_f32_e32 v115, 1.0, v115
	v_add_f32_e32 v116, 1.0, v116
	v_add_f32_e32 v117, 1.0, v117
	v_add_f32_e32 v118, 1.0, v118
	v_add_f32_e32 v119, 1.0, v119
	v_add_f32_e32 v120, 1.0, v120
	v_add_f32_e32 v121, 1.0, v121
	v_add_f32_e32 v122, 1.0, v122
	v_add_f32_e32 v123, 1.0, v123
	v_add_f32_e32 v124, 1.0, v124
	v_add_f32_e32 v125, 1.0, v125
	v_rcp_f32_e32 v110, v110
	v_rcp_f32_e32 v111, v111
	v_rcp_f32_e32 v112, v112
	v_rcp_f32_e32 v113, v113
	v_rcp_f32_e32 v114, v114
	v_rcp_f32_e32 v115, v115
	v_rcp_f32_e32 v116, v116
	v_rcp_f32_e32 v117, v117
	v_rcp_f32_e32 v118, v118
	v_rcp_f32_e32 v119, v119
	v_rcp_f32_e32 v120, v120
	v_rcp_f32_e32 v121, v121
	v_rcp_f32_e32 v122, v122
	v_rcp_f32_e32 v123, v123
	v_rcp_f32_e32 v124, v124
	v_rcp_f32_e32 v125, v125
	v_mul_f32_e32 v144, v144, v110
	v_mul_f32_e32 v145, v145, v111
	v_mul_f32_e32 v146, v146, v112
	v_mul_f32_e32 v147, v147, v113
	v_mul_f32_e32 v160, v160, v114
	v_mul_f32_e32 v161, v161, v115
	v_mul_f32_e32 v162, v162, v116
	v_mul_f32_e32 v163, v163, v117
	v_mul_f32_e32 v176, v176, v118
	v_mul_f32_e32 v177, v177, v119
; __device__ __forceinline__ float sigmoidf_(float x) { return fast_rcp(1.0f + fast_exp2(-1.4426950408889634f * x)); }
; #define KIN(i) (*(const float* const __attribute__((address_space(4)))*)(kp + kz + 8 * (i)))
; __global__ void __launch_bounds__(NTHR, 2) fwd_megakernel(Args args) {
;     ...
;                 for (int j = 0; j < 4; ++j) { const f32x4 gg = *(const f32x4*)(KIN(I_CONV_LN_G) + j * 256 + 4 * lane), bb = *(const f32x4*)(KIN(I_CONV_LN_B) + j * 256 + 4 * lane);
;                     f32x4 y = x[j] * rstd * gg + bb;
; #pragma unroll
;                     for (int e = 0; e < 4; ++e) { y[e] = y[e] * sigmoidf_(y[e]); z2 += y[e] * y[e]; }
;                     x[j] = y; }
	v_mul_f32_e32 v178, v178, v120
	v_mul_f32_e32 v179, v179, v121
	v_mul_f32_e32 v192, v192, v122
	v_mul_f32_e32 v193, v193, v123
	v_mul_f32_e32 v194, v194, v124
	v_mul_f32_e32 v195, v195, v125
	v_fmac_f32_e32 v102, v144, v144
	v_fmac_f32_e32 v103, v160, v160
	v_fmac_f32_e32 v104, v176, v176
	v_fmac_f32_e32 v105, v192, v192
	v_fmac_f32_e32 v102, v145, v145
	v_fmac_f32_e32 v103, v161, v161
	v_fmac_f32_e32 v104, v177, v177
	v_fmac_f32_e32 v105, v193, v193
	v_fmac_f32_e32 v102, v146, v146
	v_fmac_f32_e32 v103, v162, v162
	v_fmac_f32_e32 v104, v178, v178
	v_fmac_f32_e32 v105, v194, v194
	v_fmac_f32_e32 v102, v147, v147
	v_fmac_f32_e32 v103, v163, v163
	v_fmac_f32_e32 v104, v179, v179
	v_fmac_f32_e32 v105, v195, v195
	v_mul_f32_e32 v148, v148, v106
	v_mul_f32_e32 v149, v149, v106
	v_mul_f32_e32 v150, v150, v106
	v_mul_f32_e32 v151, v151, v106
	v_mul_f32_e32 v164, v164, v107
	v_mul_f32_e32 v165, v165, v107
	v_mul_f32_e32 v166, v166, v107
	v_mul_f32_e32 v167, v167, v107
	v_mul_f32_e32 v180, v180, v108
	v_mul_f32_e32 v181, v181, v108
	v_mul_f32_e32 v182, v182, v108
	v_mul_f32_e32 v183, v183, v108
	v_mul_f32_e32 v196, v196, v109
	v_mul_f32_e32 v197, v197, v109
	v_mul_f32_e32 v198, v198, v109
	v_mul_f32_e32 v199, v199, v109
	v_fma_f32 v148, v148, v212, v240
	v_fma_f32 v149, v149, v213, v241
	v_fma_f32 v150, v150, v214, v242
	v_fma_f32 v151, v151, v215, v243
	v_fma_f32 v164, v164, v212, v240
	v_fma_f32 v165, v165, v213, v241
	v_fma_f32 v166, v166, v214, v242
	v_fma_f32 v167, v167, v215, v243
	v_fma_f32 v180, v180, v212, v240
	v_fma_f32 v181, v181, v213, v241
	v_fma_f32 v182, v182, v214, v242
	v_fma_f32 v183, v183, v215, v243
	v_fma_f32 v196, v196, v212, v240
	v_fma_f32 v197, v197, v213, v241
	v_fma_f32 v198, v198, v214, v242
	v_fma_f32 v199, v199, v215, v243
	v_mul_f32_e32 v110, 0xbfb8aa3b, v148
	v_mul_f32_e32 v111, 0xbfb8aa3b, v149
	v_mul_f32_e32 v112, 0xbfb8aa3b, v150
	v_mul_f32_e32 v113, 0xbfb8aa3b, v151
	v_mul_f32_e32 v114, 0xbfb8aa3b, v164
	v_mul_f32_e32 v115, 0xbfb8aa3b, v165
	v_mul_f32_e32 v116, 0xbfb8aa3b, v166
	v_mul_f32_e32 v117, 0xbfb8aa3b, v167
	v_mul_f32_e32 v118, 0xbfb8aa3b, v180
	v_mul_f32_e32 v119, 0xbfb8aa3b, v181
	v_mul_f32_e32 v120, 0xbfb8aa3b, v182
	v_mul_f32_e32 v121, 0xbfb8aa3b, v183
	v_mul_f32_e32 v122, 0xbfb8aa3b, v196
	v_mul_f32_e32 v123, 0xbfb8aa3b, v197
	v_mul_f32_e32 v124, 0xbfb8aa3b, v198
	v_mul_f32_e32 v125, 0xbfb8aa3b, v199
	v_exp_f32_e32 v110, v110
	v_exp_f32_e32 v111, v111
	v_exp_f32_e32 v112, v112
	v_exp_f32_e32 v113, v113
	v_exp_f32_e32 v114, v114
	v_exp_f32_e32 v115, v115
	v_exp_f32_e32 v116, v116
	v_exp_f32_e32 v117, v117
	v_exp_f32_e32 v118, v118
	v_exp_f32_e32 v119, v119
	v_exp_f32_e32 v120, v120
	v_exp_f32_e32 v121, v121
	v_exp_f32_e32 v122, v122
	v_exp_f32_e32 v123, v123
	v_exp_f32_e32 v124, v124
	v_exp_f32_e32 v125, v125
	v_add_f32_e32 v110, 1.0, v110
	v_add_f32_e32 v111, 1.0, v111
	v_add_f32_e32 v112, 1.0, v112
	v_add_f32_e32 v113, 1.0, v113
	v_add_f32_e32 v114, 1.0, v114
	v_add_f32_e32 v115, 1.0, v115
	v_add_f32_e32 v116, 1.0, v116
	v_add_f32_e32 v117, 1.0, v117
	v_add_f32_e32 v118, 1.0, v118
	v_add_f32_e32 v119, 1.0, v119
	v_add_f32_e32 v120, 1.0, v120
	v_add_f32_e32 v121, 1.0, v121
	v_add_f32_e32 v122, 1.0, v122
	v_add_f32_e32 v123, 1.0, v123
	v_add_f32_e32 v124, 1.0, v124
	v_add_f32_e32 v125, 1.0, v125
	v_rcp_f32_e32 v110, v110
	v_rcp_f32_e32 v111, v111
	v_rcp_f32_e32 v112, v112
	v_rcp_f32_e32 v113, v113
	v_rcp_f32_e32 v114, v114
	v_rcp_f32_e32 v115, v115
	v_rcp_f32_e32 v116, v116
	v_rcp_f32_e32 v117, v117
	v_rcp_f32_e32 v118, v118
	v_rcp_f32_e32 v119, v119
	v_rcp_f32_e32 v120, v120
	v_rcp_f32_e32 v121, v121
	v_rcp_f32_e32 v122, v122
	v_rcp_f32_e32 v123, v123
	v_rcp_f32_e32 v124, v124
	v_rcp_f32_e32 v125, v125
	v_mul_f32_e32 v148, v148, v110
	v_mul_f32_e32 v149, v149, v111
	v_mul_f32_e32 v150, v150, v112
	v_mul_f32_e32 v151, v151, v113
	v_mul_f32_e32 v164, v164, v114
	v_mul_f32_e32 v165, v165, v115
	v_mul_f32_e32 v166, v166, v116
	v_mul_f32_e32 v167, v167, v117
	v_mul_f32_e32 v180, v180, v118
	v_mul_f32_e32 v181, v181, v119
	v_mul_f32_e32 v182, v182, v120
	v_mul_f32_e32 v183, v183, v121
	v_mul_f32_e32 v196, v196, v122
	v_mul_f32_e32 v197, v197, v123
	v_mul_f32_e32 v198, v198, v124
	v_mul_f32_e32 v199, v199, v125
	v_fmac_f32_e32 v102, v148, v148
	v_fmac_f32_e32 v103, v164, v164
	v_fmac_f32_e32 v104, v180, v180
	v_fmac_f32_e32 v105, v196, v196
	v_fmac_f32_e32 v102, v149, v149
	v_fmac_f32_e32 v103, v165, v165
	v_fmac_f32_e32 v104, v181, v181
	v_fmac_f32_e32 v105, v197, v197
	v_fmac_f32_e32 v102, v150, v150
	v_fmac_f32_e32 v103, v166, v166
	v_fmac_f32_e32 v104, v182, v182
	v_fmac_f32_e32 v105, v198, v198
	v_fmac_f32_e32 v102, v151, v151
	v_fmac_f32_e32 v103, v167, v167
	v_fmac_f32_e32 v104, v183, v183
	v_fmac_f32_e32 v105, v199, v199
	v_mul_f32_e32 v152, v152, v106
	v_mul_f32_e32 v153, v153, v106
	v_mul_f32_e32 v154, v154, v106
	v_mul_f32_e32 v155, v155, v106
	v_mul_f32_e32 v168, v168, v107
	v_mul_f32_e32 v169, v169, v107
	v_mul_f32_e32 v170, v170, v107
	v_mul_f32_e32 v171, v171, v107
	v_mul_f32_e32 v184, v184, v108
	v_mul_f32_e32 v185, v185, v108
	v_mul_f32_e32 v186, v186, v108
	v_mul_f32_e32 v187, v187, v108
	v_mul_f32_e32 v200, v200, v109
	v_mul_f32_e32 v201, v201, v109
	v_mul_f32_e32 v202, v202, v109
	v_mul_f32_e32 v203, v203, v109
	v_fma_f32 v152, v152, v228, v0
	v_fma_f32 v153, v153, v229, v1
	v_fma_f32 v154, v154, v230, v2
	v_fma_f32 v155, v155, v231, v3
	v_fma_f32 v168, v168, v228, v0
	v_fma_f32 v169, v169, v229, v1
	v_fma_f32 v170, v170, v230, v2
	v_fma_f32 v171, v171, v231, v3
	v_fma_f32 v184, v184, v228, v0
	v_fma_f32 v185, v185, v229, v1
	v_fma_f32 v186, v186, v230, v2
	v_fma_f32 v187, v187, v231, v3
; __device__ __forceinline__ float sigmoidf_(float x) { return fast_rcp(1.0f + fast_exp2(-1.4426950408889634f * x)); }
; __device__ __forceinline__ float wave_sum(float v) {
; #pragma unroll
;     for (int o = 1; o < 64; o <<= 1) v += __shfl_xor(v, o);
;     return v;
; __global__ void __launch_bounds__(NTHR, 2) fwd_megakernel(Args args) {
;     ...
;                     for (int e = 0; e < 4; ++e) { y[e] = y[e] * sigmoidf_(y[e]); z2 += y[e] * y[e]; }
;                     x[j] = y; }
;                 const float r2 = rsqrtf(wave_sum(z2) * (1.0f / CCH) + RMS_EPS);
	v_fma_f32 v200, v200, v228, v0
	v_fma_f32 v201, v201, v229, v1
	v_fma_f32 v202, v202, v230, v2
	v_fma_f32 v203, v203, v231, v3
	v_mul_f32_e32 v110, 0xbfb8aa3b, v152
	v_mul_f32_e32 v111, 0xbfb8aa3b, v153
	v_mul_f32_e32 v112, 0xbfb8aa3b, v154
	v_mul_f32_e32 v113, 0xbfb8aa3b, v155
	v_mul_f32_e32 v114, 0xbfb8aa3b, v168
	v_mul_f32_e32 v115, 0xbfb8aa3b, v169
	v_mul_f32_e32 v116, 0xbfb8aa3b, v170
	v_mul_f32_e32 v117, 0xbfb8aa3b, v171
	v_mul_f32_e32 v118, 0xbfb8aa3b, v184
	v_mul_f32_e32 v119, 0xbfb8aa3b, v185
	v_mul_f32_e32 v120, 0xbfb8aa3b, v186
	v_mul_f32_e32 v121, 0xbfb8aa3b, v187
	v_mul_f32_e32 v122, 0xbfb8aa3b, v200
	v_mul_f32_e32 v123, 0xbfb8aa3b, v201
	v_mul_f32_e32 v124, 0xbfb8aa3b, v202
	v_mul_f32_e32 v125, 0xbfb8aa3b, v203
	v_exp_f32_e32 v110, v110
	v_exp_f32_e32 v111, v111
	v_exp_f32_e32 v112, v112
	v_exp_f32_e32 v113, v113
	v_exp_f32_e32 v114, v114
	v_exp_f32_e32 v115, v115
	v_exp_f32_e32 v116, v116
	v_exp_f32_e32 v117, v117
	v_exp_f32_e32 v118, v118
	v_exp_f32_e32 v119, v119
	v_exp_f32_e32 v120, v120
	v_exp_f32_e32 v121, v121
	v_exp_f32_e32 v122, v122
	v_exp_f32_e32 v123, v123
	v_exp_f32_e32 v124, v124
	v_exp_f32_e32 v125, v125
	v_add_f32_e32 v110, 1.0, v110
	v_add_f32_e32 v111, 1.0, v111
	v_add_f32_e32 v112, 1.0, v112
	v_add_f32_e32 v113, 1.0, v113
	v_add_f32_e32 v114, 1.0, v114
	v_add_f32_e32 v115, 1.0, v115
	v_add_f32_e32 v116, 1.0, v116
	v_add_f32_e32 v117, 1.0, v117
	v_add_f32_e32 v118, 1.0, v118
	v_add_f32_e32 v119, 1.0, v119
	v_add_f32_e32 v120, 1.0, v120
	v_add_f32_e32 v121, 1.0, v121
	v_add_f32_e32 v122, 1.0, v122
	v_add_f32_e32 v123, 1.0, v123
	v_add_f32_e32 v124, 1.0, v124
	v_add_f32_e32 v125, 1.0, v125
	v_rcp_f32_e32 v110, v110
	v_rcp_f32_e32 v111, v111
	v_rcp_f32_e32 v112, v112
	v_rcp_f32_e32 v113, v113
	v_rcp_f32_e32 v114, v114
	v_rcp_f32_e32 v115, v115
	v_rcp_f32_e32 v116, v116
	v_rcp_f32_e32 v117, v117
	v_rcp_f32_e32 v118, v118
	v_rcp_f32_e32 v119, v119
	v_rcp_f32_e32 v120, v120
	v_rcp_f32_e32 v121, v121
	v_rcp_f32_e32 v122, v122
	v_rcp_f32_e32 v123, v123
	v_rcp_f32_e32 v124, v124
	v_rcp_f32_e32 v125, v125
	v_mul_f32_e32 v152, v152, v110
	v_mul_f32_e32 v153, v153, v111
	v_mul_f32_e32 v154, v154, v112
	v_mul_f32_e32 v155, v155, v113
	v_mul_f32_e32 v168, v168, v114
	v_mul_f32_e32 v169, v169, v115
	v_mul_f32_e32 v170, v170, v116
	v_mul_f32_e32 v171, v171, v117
	v_mul_f32_e32 v184, v184, v118
	v_mul_f32_e32 v185, v185, v119
	v_mul_f32_e32 v186, v186, v120
	v_mul_f32_e32 v187, v187, v121
	v_mul_f32_e32 v200, v200, v122
	v_mul_f32_e32 v201, v201, v123
	v_mul_f32_e32 v202, v202, v124
	v_mul_f32_e32 v203, v203, v125
	v_fmac_f32_e32 v102, v152, v152
	v_fmac_f32_e32 v103, v168, v168
	v_fmac_f32_e32 v104, v184, v184
	v_fmac_f32_e32 v105, v200, v200
	v_fmac_f32_e32 v102, v153, v153
	v_fmac_f32_e32 v103, v169, v169
	v_fmac_f32_e32 v104, v185, v185
	v_fmac_f32_e32 v105, v201, v201
	v_fmac_f32_e32 v102, v154, v154
	v_fmac_f32_e32 v103, v170, v170
	v_fmac_f32_e32 v104, v186, v186
	v_fmac_f32_e32 v105, v202, v202
	v_fmac_f32_e32 v102, v155, v155
	v_fmac_f32_e32 v103, v171, v171
	v_fmac_f32_e32 v104, v187, v187
	v_fmac_f32_e32 v105, v203, v203
	s_nop 1
	v_add_f32_dpp v98, v102, v102 quad_perm:[1,0,3,2] row_mask:0xf bank_mask:0xf
	v_add_f32_dpp v99, v103, v103 quad_perm:[1,0,3,2] row_mask:0xf bank_mask:0xf
	v_add_f32_dpp v100, v104, v104 quad_perm:[1,0,3,2] row_mask:0xf bank_mask:0xf
	v_add_f32_dpp v101, v105, v105 quad_perm:[1,0,3,2] row_mask:0xf bank_mask:0xf
	v_mov_b32_e32 v102, v98
	v_mov_b32_e32 v103, v99
	v_mov_b32_e32 v104, v100
	v_mov_b32_e32 v105, v101
	s_nop 1
	v_add_f32_dpp v98, v102, v102 quad_perm:[2,3,0,1] row_mask:0xf bank_mask:0xf
	v_add_f32_dpp v99, v103, v103 quad_perm:[2,3,0,1] row_mask:0xf bank_mask:0xf
	v_add_f32_dpp v100, v104, v104 quad_perm:[2,3,0,1] row_mask:0xf bank_mask:0xf
	v_add_f32_dpp v101, v105, v105 quad_perm:[2,3,0,1] row_mask:0xf bank_mask:0xf
	v_mov_b32_e32 v102, v98
	v_mov_b32_e32 v103, v99
	v_mov_b32_e32 v104, v100
	v_mov_b32_e32 v105, v101
	s_nop 1
	v_add_f32_dpp v98, v102, v102 row_half_mirror row_mask:0xf bank_mask:0xf
	v_add_f32_dpp v99, v103, v103 row_half_mirror row_mask:0xf bank_mask:0xf
	v_add_f32_dpp v100, v104, v104 row_half_mirror row_mask:0xf bank_mask:0xf
	v_add_f32_dpp v101, v105, v105 row_half_mirror row_mask:0xf bank_mask:0xf
	v_mov_b32_e32 v102, v98
	v_mov_b32_e32 v103, v99
	v_mov_b32_e32 v104, v100
	v_mov_b32_e32 v105, v101
	s_nop 1
	v_add_f32_dpp v98, v102, v102 row_mirror row_mask:0xf bank_mask:0xf
	v_add_f32_dpp v99, v103, v103 row_mirror row_mask:0xf bank_mask:0xf
	v_add_f32_dpp v100, v104, v104 row_mirror row_mask:0xf bank_mask:0xf
	v_add_f32_dpp v101, v105, v105 row_mirror row_mask:0xf bank_mask:0xf
	v_mov_b32_e32 v102, v98
	v_mov_b32_e32 v103, v99
	v_mov_b32_e32 v104, v100
	v_mov_b32_e32 v105, v101
	v_mov_b32_e32 v98, v102
	v_mov_b32_e32 v99, v103
	v_mov_b32_e32 v100, v104
	v_mov_b32_e32 v101, v105
	s_nop 1
	v_permlane16_swap_b32_e32 v102, v98
	v_permlane16_swap_b32_e32 v103, v99
	v_permlane16_swap_b32_e32 v104, v100
	v_permlane16_swap_b32_e32 v105, v101
	s_nop 1
	v_add_f32_e32 v102, v102, v98
	v_add_f32_e32 v103, v103, v99
	v_add_f32_e32 v104, v104, v100
	v_add_f32_e32 v105, v105, v101
	v_mov_b32_e32 v98, v102
	v_mov_b32_e32 v99, v103
	v_mov_b32_e32 v100, v104
	v_mov_b32_e32 v101, v105
	s_nop 1
	v_permlane32_swap_b32_e32 v102, v98
	v_permlane32_swap_b32_e32 v103, v99
	v_permlane32_swap_b32_e32 v104, v100
	v_permlane32_swap_b32_e32 v105, v101
	s_nop 1
	v_add_f32_e32 v102, v102, v98
	v_add_f32_e32 v103, v103, v99
	v_add_f32_e32 v104, v104, v100
	v_add_f32_e32 v105, v105, v101
	v_fmamk_f32 v106, v102, 0x3a800000, v227
	v_fmamk_f32 v107, v103, 0x3a800000, v227
; __device__ __forceinline__ unsigned cvt_pk_bf16(float lo, float hi) { unsigned r; asm volatile("v_cvt_pk_bf16_f32 %0, %1, %2" : "=v"(r) : "v"(lo), "v"(hi)); return r; }
; #define KIN(i) (*(const float* const __attribute__((address_space(4)))*)(kp + kz + 8 * (i)))
; __global__ void __launch_bounds__(NTHR, 2) fwd_megakernel(Args args) {
;     ...
;         for (int cu = bid; cu < T / 32; cu += G) {
;     ...
;                 const float r2 = rsqrtf(wave_sum(z2) * (1.0f / CCH) + RMS_EPS);
; #pragma unroll
;                 for (int j = 0; j < 4; ++j) { const f32x4 gg = *(const f32x4*)(KIN(I_OUT_NORM_CONV) + j * 256 + 4 * lane); const f32x4 y = x[j] * r2 * gg;
;                     u32x2 w; w.x = cvt_pk_bf16(y[0], y[1]); w.y = cvt_pk_bf16(y[2], y[3]); *(u32x2*)(Y + (size_t)(t0 + r) * D + j * 256 + 4 * lane) = w; }
;             }
;             __syncthreads();
;         }
	v_fmamk_f32 v108, v104, 0x3a800000, v227
	v_fmamk_f32 v109, v105, 0x3a800000, v227
	v_rsq_f32_e32 v106, v106
	v_rsq_f32_e32 v107, v107
	v_rsq_f32_e32 v108, v108
	v_rsq_f32_e32 v109, v109
	s_nop 0
	v_mul_f32_e32 v140, v140, v106
	v_mul_f32_e32 v141, v141, v106
	v_mul_f32_e32 v142, v142, v106
	v_mul_f32_e32 v143, v143, v106
	v_mul_f32_e32 v156, v156, v107
	v_mul_f32_e32 v157, v157, v107
	v_mul_f32_e32 v158, v158, v107
	v_mul_f32_e32 v159, v159, v107
	v_mul_f32_e32 v172, v172, v108
	v_mul_f32_e32 v173, v173, v108
	v_mul_f32_e32 v174, v174, v108
	v_mul_f32_e32 v175, v175, v108
	v_mul_f32_e32 v188, v188, v109
	v_mul_f32_e32 v189, v189, v109
	v_mul_f32_e32 v190, v190, v109
	v_mul_f32_e32 v191, v191, v109
	v_mul_f32_e32 v140, v140, v4
	v_mul_f32_e32 v141, v141, v5
	v_mul_f32_e32 v142, v142, v6
	v_mul_f32_e32 v143, v143, v7
	v_mul_f32_e32 v156, v156, v4
	v_mul_f32_e32 v157, v157, v5
	v_mul_f32_e32 v158, v158, v6
	v_mul_f32_e32 v159, v159, v7
	v_mul_f32_e32 v172, v172, v4
	v_mul_f32_e32 v173, v173, v5
	v_mul_f32_e32 v174, v174, v6
	v_mul_f32_e32 v175, v175, v7
	v_mul_f32_e32 v188, v188, v4
	v_mul_f32_e32 v189, v189, v5
	v_mul_f32_e32 v190, v190, v6
	v_mul_f32_e32 v191, v191, v7
	v_mul_f32_e32 v144, v144, v106
	v_mul_f32_e32 v145, v145, v106
	v_mul_f32_e32 v146, v146, v106
	v_mul_f32_e32 v147, v147, v106
	v_mul_f32_e32 v160, v160, v107
	v_mul_f32_e32 v161, v161, v107
	v_mul_f32_e32 v162, v162, v107
	v_mul_f32_e32 v163, v163, v107
	v_mul_f32_e32 v176, v176, v108
	v_mul_f32_e32 v177, v177, v108
	v_mul_f32_e32 v178, v178, v108
	v_mul_f32_e32 v179, v179, v108
	v_mul_f32_e32 v192, v192, v109
	v_mul_f32_e32 v193, v193, v109
	v_mul_f32_e32 v194, v194, v109
	v_mul_f32_e32 v195, v195, v109
	v_mul_f32_e32 v144, v144, v8
	v_mul_f32_e32 v145, v145, v9
	v_mul_f32_e32 v146, v146, v10
	v_mul_f32_e32 v147, v147, v11
	v_mul_f32_e32 v160, v160, v8
	v_mul_f32_e32 v161, v161, v9
	v_mul_f32_e32 v162, v162, v10
	v_mul_f32_e32 v163, v163, v11
	v_mul_f32_e32 v176, v176, v8
	v_mul_f32_e32 v177, v177, v9
	v_mul_f32_e32 v178, v178, v10
	v_mul_f32_e32 v179, v179, v11
	v_mul_f32_e32 v192, v192, v8
	v_mul_f32_e32 v193, v193, v9
	v_mul_f32_e32 v194, v194, v10
	v_mul_f32_e32 v195, v195, v11
	v_cvt_pk_bf16_f32 v140, v140, v141
	v_cvt_pk_bf16_f32 v141, v142, v143
	v_cvt_pk_bf16_f32 v142, v144, v145
	v_cvt_pk_bf16_f32 v143, v146, v147
	v_cvt_pk_bf16_f32 v156, v156, v157
	v_cvt_pk_bf16_f32 v157, v158, v159
	v_cvt_pk_bf16_f32 v158, v160, v161
	v_cvt_pk_bf16_f32 v159, v162, v163
	v_cvt_pk_bf16_f32 v172, v172, v173
	v_cvt_pk_bf16_f32 v173, v174, v175
	v_cvt_pk_bf16_f32 v174, v176, v177
	v_cvt_pk_bf16_f32 v175, v178, v179
	v_cvt_pk_bf16_f32 v188, v188, v189
	v_cvt_pk_bf16_f32 v189, v190, v191
	v_cvt_pk_bf16_f32 v190, v192, v193
	v_cvt_pk_bf16_f32 v191, v194, v195
	global_store_dwordx4 v[126:127], v[140:143], off
	global_store_dwordx4 v[128:129], v[156:159], off
	global_store_dwordx4 v[130:131], v[172:175], off
	global_store_dwordx4 v[132:133], v[188:191], off
	v_mul_f32_e32 v148, v148, v106
	v_mul_f32_e32 v149, v149, v106
	v_mul_f32_e32 v150, v150, v106
	v_mul_f32_e32 v151, v151, v106
	v_mul_f32_e32 v164, v164, v107
	v_mul_f32_e32 v165, v165, v107
	v_mul_f32_e32 v166, v166, v107
	v_mul_f32_e32 v167, v167, v107
	v_mul_f32_e32 v180, v180, v108
	v_mul_f32_e32 v181, v181, v108
	v_mul_f32_e32 v182, v182, v108
	v_mul_f32_e32 v183, v183, v108
	v_mul_f32_e32 v196, v196, v109
	v_mul_f32_e32 v197, v197, v109
	v_mul_f32_e32 v198, v198, v109
	v_mul_f32_e32 v199, v199, v109
	v_mul_f32_e32 v148, v148, v12
	v_mul_f32_e32 v149, v149, v13
	v_mul_f32_e32 v150, v150, v14
	v_mul_f32_e32 v151, v151, v15
	v_mul_f32_e32 v164, v164, v12
	v_mul_f32_e32 v165, v165, v13
	v_mul_f32_e32 v166, v166, v14
	v_mul_f32_e32 v167, v167, v15
	v_mul_f32_e32 v180, v180, v12
	v_mul_f32_e32 v181, v181, v13
	v_mul_f32_e32 v182, v182, v14
	v_mul_f32_e32 v183, v183, v15
	v_mul_f32_e32 v196, v196, v12
	v_mul_f32_e32 v197, v197, v13
	v_mul_f32_e32 v198, v198, v14
	v_mul_f32_e32 v199, v199, v15
	v_mul_f32_e32 v152, v152, v106
	v_mul_f32_e32 v153, v153, v106
	v_mul_f32_e32 v154, v154, v106
	v_mul_f32_e32 v155, v155, v106
	v_mul_f32_e32 v168, v168, v107
	v_mul_f32_e32 v169, v169, v107
	v_mul_f32_e32 v170, v170, v107
	v_mul_f32_e32 v171, v171, v107
	v_mul_f32_e32 v184, v184, v108
	v_mul_f32_e32 v185, v185, v108
	v_mul_f32_e32 v186, v186, v108
	v_mul_f32_e32 v187, v187, v108
	v_mul_f32_e32 v200, v200, v109
	v_mul_f32_e32 v201, v201, v109
	v_mul_f32_e32 v202, v202, v109
	v_mul_f32_e32 v203, v203, v109
	v_mul_f32_e32 v152, v152, v16
	v_mul_f32_e32 v153, v153, v17
	v_mul_f32_e32 v154, v154, v18
	v_mul_f32_e32 v155, v155, v19
	v_mul_f32_e32 v168, v168, v16
	v_mul_f32_e32 v169, v169, v17
	v_mul_f32_e32 v170, v170, v18
	v_mul_f32_e32 v171, v171, v19
	v_mul_f32_e32 v184, v184, v16
	v_mul_f32_e32 v185, v185, v17
	v_mul_f32_e32 v186, v186, v18
	v_mul_f32_e32 v187, v187, v19
	v_mul_f32_e32 v200, v200, v16
	v_mul_f32_e32 v201, v201, v17
	v_mul_f32_e32 v202, v202, v18
	v_mul_f32_e32 v203, v203, v19
	v_cvt_pk_bf16_f32 v148, v148, v149
	v_cvt_pk_bf16_f32 v149, v150, v151
	v_cvt_pk_bf16_f32 v150, v152, v153
	v_cvt_pk_bf16_f32 v151, v154, v155
	v_cvt_pk_bf16_f32 v164, v164, v165
	v_cvt_pk_bf16_f32 v165, v166, v167
	v_cvt_pk_bf16_f32 v166, v168, v169
	v_cvt_pk_bf16_f32 v167, v170, v171
	v_cvt_pk_bf16_f32 v180, v180, v181
	v_cvt_pk_bf16_f32 v181, v182, v183
	v_cvt_pk_bf16_f32 v182, v184, v185
	v_cvt_pk_bf16_f32 v183, v186, v187
	v_cvt_pk_bf16_f32 v196, v196, v197
	v_cvt_pk_bf16_f32 v197, v198, v199
	v_cvt_pk_bf16_f32 v198, v200, v201
	v_cvt_pk_bf16_f32 v199, v202, v203
	global_store_dwordx4 v[126:127], v[148:151], off offset:1024
	global_store_dwordx4 v[128:129], v[164:167], off offset:1024
	global_store_dwordx4 v[130:131], v[180:183], off offset:1024
	global_store_dwordx4 v[132:133], v[196:199], off offset:1024
	s_add_i32 s61, s61, s34
	s_cmpk_gt_i32 s61, 0xff
	s_barrier
	s_cbranch_scc1 .LBB0_657
